# v60 + P5 EpiOut XN stores written through (sc1) so the write-back overlaps the epilogue rather than the grid barrier flush
# speedup vs baseline: 1.0061x; 1.0022x over previous
; __device__ __forceinline__ unsigned cvt_pk_bf16(float lo, float hi) { unsigned r; asm volatile("v_cvt_pk_bf16_f32 %0, %1, %2" : "=v"(r) : "v"(lo), "v"(hi)); return r; }
;     __device__ __forceinline__ void operator()(const pg8::f32x4 (&acc)[2][2][4][2], const Unit& u, int wr, int wc, int fr, int fq) const {
;         const int row0 = u.pm * BM + wr * 64, lane = fr + 16 * fq, rr = lane >> 3, sl = lane & 7;
;         LAS unsigned char* W = scr + (wr * 4 + wc) * 2048;
;         const float* xb = xp + (size_t)(row0 + rr) * DM + (size_t)u.pn * BM + wc * 32 + 4 * sl;
;         bf16* ob = XN + (size_t)(row0 + rr) * DM + (size_t)u.pn * BM + wc * 32 + 4 * sl;
;         pg8::f32x4 xc[2][2], xn[2][2];
; #pragma unroll
;         for (int bj = 0; bj < 2; ++bj)
; #pragma unroll
;             for (int p = 0; p < 2; ++p) xc[bj][p] = *(const pg8::f32x4*)(xb + (size_t)(8 * p) * DM + bj * HALF);
; #pragma unroll
;         for (int g = 0; g < 8; ++g) { const int ai = g >> 2, m = g & 3, rg = ai * HALF + m * 16; float s0 = 0.f, s1 = 0.f;
;             if (g < 7) { const int rgn = ((g + 1) >> 2) * HALF + ((g + 1) & 3) * 16;
; #pragma unroll
;                 for (int bj = 0; bj < 2; ++bj)
; #pragma unroll
;                     for (int p = 0; p < 2; ++p) xn[bj][p] = *(const pg8::f32x4*)(xb + (size_t)(rgn + 8 * p) * DM + bj * HALF); }
; #pragma unroll
;             for (int bj = 0; bj < 2; ++bj) { *(LAS pg8::f32x4*)epi_slot(W, fr, 2 * fq) = acc[ai][bj][m][0]; *(LAS pg8::f32x4*)epi_slot(W, fr, 2 * fq + 1) = acc[ai][bj][m][1];
; #pragma unroll
;                 for (int p = 0; p < 2; ++p) { const pg8::f32x4 x1 = xc[bj][p] + *(const LAS pg8::f32x4*)epi_slot(W, 8 * p + rr, sl);
;                     const float q = (x1[0] * x1[0] + x1[1] * x1[1]) + (x1[2] * x1[2] + x1[3] * x1[3]); if (p == 0) s0 += q; else s1 += q;
;                     v2u w; w.x = cvt_pk_bf16(x1[0], x1[1]); w.y = cvt_pk_bf16(x1[2], x1[3]); *(v2u*)(ob + (size_t)(rg + 8 * p) * DM + bj * HALF) = w; } }
;             s0 += __shfl_xor(s0, 1); s1 += __shfl_xor(s1, 1); s0 += __shfl_xor(s0, 2); s1 += __shfl_xor(s1, 2); s0 += __shfl_xor(s0, 4); s1 += __shfl_xor(s1, 4);
;             if (sl == 0) { __hip_atomic_fetch_add(SS1 + row0 + rg + rr, s0, __ATOMIC_RELAXED, __HIP_MEMORY_SCOPE_AGENT); __hip_atomic_fetch_add(SS1 + row0 + rg + 8 + rr, s1, __ATOMIC_RELAXED, __HIP_MEMORY_SCOPE_AGENT); }
.LBB0_786:
	s_lshl_b32 s5, s20, 8
	s_add_i32 s38, s5, s58
	v_or_b32_e32 v180, s38, v185
	v_ashrrev_i32_e32 v181, 31, v180
	v_readlane_b32 s76, v238, 4
	v_lshlrev_b64 v[130:131], 12, v[180:181]
	v_readlane_b32 s77, v238, 5
	s_ashr_i32 s5, s4, 31
	s_lshl_b64 s[40:41], s[4:5], 10
	v_lshl_add_u64 v[130:131], s[76:77], 0, v[130:131]
	v_lshl_add_u64 v[130:131], v[130:131], 0, s[40:41]
	s_lshl_b32 s20, s59, 2
	v_lshl_add_u64 v[130:131], v[130:131], 0, s[20:21]
	v_lshlrev_b32_e32 v164, 2, v166
	v_lshl_add_u64 v[178:179], v[130:131], 0, v[164:165]
	global_load_dwordx4 v[142:145], v[178:179], off nt
	v_add_co_u32_e32 v130, vcc, s68, v178
	v_xor_b32_e32 v164, 1, v189
	s_nop 0
	v_addc_co_u32_e32 v131, vcc, 0, v179, vcc
	global_load_dwordx4 v[138:141], v[130:131], off nt
	global_load_dwordx4 v[134:137], v[178:179], off offset:512 nt
	s_nop 0
	global_load_dwordx4 v[130:133], v[130:131], off offset:512 nt
	ds_write_b128 v190, v[126:129]
	ds_write_b128 v191, v[122:125]
	v_and_b32_e32 v122, 64, v189
	v_add_u32_e32 v202, 64, v122
	v_add_co_u32_e32 v122, vcc, s55, v178
	ds_read_b128 v[194:197], v192
	s_nop 0
	v_addc_co_u32_e32 v123, vcc, 0, v179, vcc
	v_add_co_u32_e32 v124, vcc, s63, v178
	v_lshlrev_b64 v[180:181], 11, v[180:181]
	s_nop 0
	v_addc_co_u32_e32 v125, vcc, 0, v179, vcc
	global_load_dwordx4 v[150:153], v[122:123], off nt
	global_load_dwordx4 v[126:129], v[122:123], off offset:512 nt
	global_load_dwordx4 v[146:149], v[124:125], off nt
	s_nop 0
	global_load_dwordx4 v[122:125], v[124:125], off offset:512 nt
	s_lshl_b64 s[4:5], s[4:5], 9
	v_cmp_lt_i32_e32 vcc, v164, v202
	v_lshl_add_u64 v[180:181], s[46:47], 0, v[180:181]
	v_lshl_add_u64 v[180:181], v[180:181], 0, s[4:5]
	v_cndmask_b32_e32 v164, v189, v164, vcc
	s_lshl_b32 s20, s59, 1
	v_lshlrev_b32_e32 v193, 2, v164
	v_lshl_add_u64 v[180:181], v[180:181], 0, s[20:21]
	v_lshlrev_b32_e32 v164, 1, v166
	v_lshl_add_u64 v[180:181], v[180:181], 0, v[164:165]
	s_movk_i32 s29, 0x4000
	v_add_co_u32_e32 v182, vcc, s29, v180
	v_xor_b32_e32 v200, 2, v189
	s_nop 0
	v_addc_co_u32_e32 v183, vcc, 0, v181, vcc
	v_cmp_lt_i32_e32 vcc, v200, v202
	v_xor_b32_e32 v201, 4, v189
	s_ashr_i32 s39, s38, 31
	v_readlane_b32 s78, v238, 6
	v_readlane_b32 s79, v238, 7
	v_readlane_b32 s80, v238, 8
	v_readlane_b32 s81, v238, 9
	v_readlane_b32 s82, v238, 10
	v_readlane_b32 s83, v238, 11
	v_readlane_b32 s84, v238, 12
	v_readlane_b32 s85, v238, 13
	v_readlane_b32 s86, v238, 14
	v_readlane_b32 s87, v238, 15
	v_readlane_b32 s88, v238, 16
	v_readlane_b32 s89, v238, 17
	v_readlane_b32 s90, v238, 18
	v_readlane_b32 s91, v238, 19
	s_waitcnt vmcnt(0) lgkmcnt(0)
	v_pk_add_f32 v[196:197], v[144:145], v[196:197]
	v_pk_add_f32 v[194:195], v[142:143], v[194:195]
	v_mul_f32_e32 v203, v197, v197
	v_cvt_pk_bf16_f32 v198, v194, v195
	v_cvt_pk_bf16_f32 v199, v196, v197
	ds_read_b128 v[142:145], v192 offset:1024
	global_store_dwordx2 v[180:181], v[198:199], off sc1
	v_mul_f32_e32 v164, v195, v195
	v_fmac_f32_e32 v164, v194, v194
	v_fmac_f32_e32 v203, v196, v196
	s_waitcnt lgkmcnt(0)
	v_pk_add_f32 v[140:141], v[140:141], v[144:145]
	v_pk_add_f32 v[138:139], v[138:139], v[142:143]
	v_add_f32_e32 v164, v164, v203
	v_cvt_pk_bf16_f32 v142, v138, v139
	v_cvt_pk_bf16_f32 v143, v140, v141
	ds_write_b128 v190, v[118:121]
	ds_write_b128 v191, v[114:117]
	ds_read_b128 v[114:117], v192
	global_store_dwordx2 v[182:183], v[142:143], off sc1
	v_mul_f32_e32 v144, v139, v139
	v_fmac_f32_e32 v144, v138, v138
	v_mul_f32_e32 v145, v141, v141
	s_waitcnt lgkmcnt(0)
	v_pk_add_f32 v[116:117], v[136:137], v[116:117]
	v_pk_add_f32 v[114:115], v[134:135], v[114:115]
	v_mul_f32_e32 v138, v117, v117
	v_cvt_pk_bf16_f32 v118, v114, v115
	v_cvt_pk_bf16_f32 v119, v116, v117
	ds_read_b128 v[134:137], v192 offset:1024
	v_mul_f32_e32 v121, v115, v115
	v_fmac_f32_e32 v121, v114, v114
	v_fmac_f32_e32 v138, v116, v116
	v_add_f32_e32 v114, v121, v138
	v_add_f32_e32 v121, v164, v114
	s_waitcnt lgkmcnt(0)
	v_pk_add_f32 v[114:115], v[132:133], v[136:137]
	v_pk_add_f32 v[116:117], v[130:131], v[134:135]
	v_mul_f32_e32 v131, v115, v115
	v_mul_f32_e32 v130, v117, v117
	v_fmac_f32_e32 v145, v140, v140
	v_fmac_f32_e32 v130, v116, v116
	v_fmac_f32_e32 v131, v114, v114
	v_add_f32_e32 v120, v144, v145
	v_add_f32_e32 v130, v130, v131
	v_add_f32_e32 v120, v120, v130
	ds_bpermute_b32 v138, v193, v121
	ds_bpermute_b32 v130, v193, v120
	v_cndmask_b32_e32 v131, v189, v200, vcc
	v_lshlrev_b32_e32 v140, 2, v131
	v_cmp_lt_i32_e32 vcc, v201, v202
	s_waitcnt lgkmcnt(1)
	v_add_f32_e32 v121, v121, v138
	s_waitcnt lgkmcnt(0)
	v_add_f32_e32 v120, v120, v130
	ds_bpermute_b32 v131, v140, v121
	ds_bpermute_b32 v130, v140, v120
	v_cndmask_b32_e32 v132, v189, v201, vcc
	v_lshlrev_b32_e32 v141, 2, v132
	global_store_dwordx2 v[180:181], v[118:119], off offset:256 sc1
	s_waitcnt lgkmcnt(1)
	v_add_f32_e32 v118, v121, v131
	s_waitcnt lgkmcnt(0)
	v_add_f32_e32 v119, v120, v130
	ds_bpermute_b32 v120, v141, v118
	ds_bpermute_b32 v121, v141, v119
	v_lshl_add_u64 v[138:139], s[38:39], 2, v[168:169]
	v_cvt_pk_bf16_f32 v116, v116, v117
	v_cvt_pk_bf16_f32 v117, v114, v115
	global_store_dwordx2 v[182:183], v[116:117], off offset:256 sc1
	s_and_saveexec_b64 s[4:5], s[0:1]
	s_cbranch_execz .LBB0_788
	s_waitcnt lgkmcnt(1)
	v_add_f32_e32 v114, v118, v120
	s_waitcnt lgkmcnt(0)
	v_add_f32_e32 v115, v119, v121
	global_atomic_add_f32 v[138:139], v114, off
	global_atomic_add_f32 v[138:139], v115, off offset:32
; __device__ __forceinline__ unsigned cvt_pk_bf16(float lo, float hi) { unsigned r; asm volatile("v_cvt_pk_bf16_f32 %0, %1, %2" : "=v"(r) : "v"(lo), "v"(hi)); return r; }
; #define LAS __attribute__((address_space(3)))
;     __device__ __forceinline__ void operator()(const pg8::f32x4 (&acc)[2][2][4][2], const Unit& u, int wr, int wc, int fr, int fq) const {
;     ...
;         for (int g = 0; g < 8; ++g) { const int ai = g >> 2, m = g & 3, rg = ai * HALF + m * 16; float s0 = 0.f, s1 = 0.f;
;             if (g < 7) { const int rgn = ((g + 1) >> 2) * HALF + ((g + 1) & 3) * 16;
; #pragma unroll
;                 for (int bj = 0; bj < 2; ++bj)
; #pragma unroll
;                     for (int p = 0; p < 2; ++p) xn[bj][p] = *(const pg8::f32x4*)(xb + (size_t)(rgn + 8 * p) * DM + bj * HALF); }
; #pragma unroll
;             for (int bj = 0; bj < 2; ++bj) { *(LAS pg8::f32x4*)epi_slot(W, fr, 2 * fq) = acc[ai][bj][m][0]; *(LAS pg8::f32x4*)epi_slot(W, fr, 2 * fq + 1) = acc[ai][bj][m][1];
; #pragma unroll
;                 for (int p = 0; p < 2; ++p) { const pg8::f32x4 x1 = xc[bj][p] + *(const LAS pg8::f32x4*)epi_slot(W, 8 * p + rr, sl);
;                     const float q = (x1[0] * x1[0] + x1[1] * x1[1]) + (x1[2] * x1[2] + x1[3] * x1[3]); if (p == 0) s0 += q; else s1 += q;
;                     v2u w; w.x = cvt_pk_bf16(x1[0], x1[1]); w.y = cvt_pk_bf16(x1[2], x1[3]); *(v2u*)(ob + (size_t)(rg + 8 * p) * DM + bj * HALF) = w; } }
;             s0 += __shfl_xor(s0, 1); s1 += __shfl_xor(s1, 1); s0 += __shfl_xor(s0, 2); s1 += __shfl_xor(s1, 2); s0 += __shfl_xor(s0, 4); s1 += __shfl_xor(s1, 4);
;             if (sl == 0) { __hip_atomic_fetch_add(SS1 + row0 + rg + rr, s0, __ATOMIC_RELAXED, __HIP_MEMORY_SCOPE_AGENT); __hip_atomic_fetch_add(SS1 + row0 + rg + 8 + rr, s1, __ATOMIC_RELAXED, __HIP_MEMORY_SCOPE_AGENT); }
; #pragma unroll
;             for (int bj = 0; bj < 2; ++bj)
; #pragma unroll
;                 for (int p = 0; p < 2; ++p) xc[bj][p] = xn[bj][p]; }
.LBB0_788:
	s_or_b64 exec, exec, s[4:5]
	v_add_co_u32_e32 v114, vcc, 0x20000, v178
	s_mov_b32 s4, 0xc000
	s_nop 0
	v_addc_co_u32_e32 v115, vcc, 0, v179, vcc
	v_add_co_u32_e32 v116, vcc, 0x28000, v178
	s_nop 1
	v_addc_co_u32_e32 v117, vcc, 0, v179, vcc
	global_load_dwordx4 v[134:137], v[114:115], off nt
	s_waitcnt lgkmcnt(0)
	global_load_dwordx4 v[118:121], v[114:115], off offset:512 nt
	global_load_dwordx4 v[130:133], v[116:117], off nt
	s_nop 0
	global_load_dwordx4 v[114:117], v[116:117], off offset:512 nt
	ds_write_b128 v190, v[110:113]
	ds_write_b128 v191, v[106:109]
	ds_read_b128 v[106:109], v192
	v_add_co_u32_e32 v112, vcc, s68, v180
	s_waitcnt lgkmcnt(0)
	v_pk_add_f32 v[108:109], v[152:153], v[108:109]
	v_pk_add_f32 v[106:107], v[150:151], v[106:107]
	v_mul_f32_e32 v111, v109, v109
	v_mul_f32_e32 v110, v107, v107
	v_fmac_f32_e32 v110, v106, v106
	v_fmac_f32_e32 v111, v108, v108
	v_add_f32_e32 v142, v110, v111
	v_cvt_pk_bf16_f32 v110, v106, v107
	v_cvt_pk_bf16_f32 v111, v108, v109
	ds_read_b128 v[106:109], v192 offset:1024
	v_addc_co_u32_e32 v113, vcc, 0, v181, vcc
	global_store_dwordx2 v[112:113], v[110:111], off sc1
	s_waitcnt lgkmcnt(0)
	v_pk_add_f32 v[106:107], v[146:147], v[106:107]
	s_nop 0
	v_mul_f32_e32 v110, v107, v107
	v_pk_add_f32 v[108:109], v[148:149], v[108:109]
	v_fmac_f32_e32 v110, v106, v106
	v_cvt_pk_bf16_f32 v106, v106, v107
	v_cvt_pk_bf16_f32 v107, v108, v109
	ds_write_b128 v190, v[102:105]
	ds_write_b128 v191, v[98:101]
	ds_read_b128 v[98:101], v192
	v_mul_f32_e32 v111, v109, v109
	v_add_co_u32_e32 v102, vcc, s4, v180
	v_fmac_f32_e32 v111, v108, v108
	s_waitcnt lgkmcnt(0)
	v_pk_add_f32 v[98:99], v[126:127], v[98:99]
	v_addc_co_u32_e32 v103, vcc, 0, v181, vcc
	v_mul_f32_e32 v108, v99, v99
	global_store_dwordx2 v[102:103], v[106:107], off sc1
	v_pk_add_f32 v[104:105], v[128:129], v[100:101]
	v_fmac_f32_e32 v108, v98, v98
	v_cvt_pk_bf16_f32 v106, v98, v99
	v_cvt_pk_bf16_f32 v107, v104, v105
	ds_read_b128 v[98:101], v192 offset:1024
	v_mul_f32_e32 v105, v105, v105
	v_fmac_f32_e32 v105, v104, v104
	v_add_f32_e32 v104, v108, v105
	v_add_f32_e32 v110, v110, v111
	v_add_f32_e32 v111, v142, v104
	s_waitcnt lgkmcnt(0)
	v_pk_add_f32 v[104:105], v[124:125], v[100:101]
	v_pk_add_f32 v[108:109], v[122:123], v[98:99]
	v_mul_f32_e32 v99, v105, v105
	v_mul_f32_e32 v98, v109, v109
	v_fmac_f32_e32 v98, v108, v108
	v_fmac_f32_e32 v99, v104, v104
	v_add_f32_e32 v98, v98, v99
	v_add_f32_e32 v98, v110, v98
	ds_bpermute_b32 v99, v193, v111
	ds_bpermute_b32 v100, v193, v98
	global_store_dwordx2 v[112:113], v[106:107], off offset:256 sc1
	v_cvt_pk_bf16_f32 v106, v108, v109
	v_cvt_pk_bf16_f32 v107, v104, v105
	s_waitcnt lgkmcnt(1)
	v_add_f32_e32 v99, v111, v99
	s_waitcnt lgkmcnt(0)
	v_add_f32_e32 v100, v98, v100
	ds_bpermute_b32 v98, v140, v99
	ds_bpermute_b32 v101, v140, v100
	global_store_dwordx2 v[102:103], v[106:107], off offset:256 sc1
	s_waitcnt lgkmcnt(1)
	v_add_f32_e32 v98, v99, v98
	s_waitcnt lgkmcnt(0)
	v_add_f32_e32 v99, v100, v101
	ds_bpermute_b32 v100, v141, v98
	ds_bpermute_b32 v101, v141, v99
	s_and_saveexec_b64 s[4:5], s[0:1]
	s_cbranch_execz .LBB0_790
	s_waitcnt lgkmcnt(1)
	v_add_f32_e32 v98, v98, v100
	s_waitcnt lgkmcnt(0)
	v_add_f32_e32 v99, v99, v101
	global_atomic_add_f32 v[138:139], v98, off offset:64
	global_atomic_add_f32 v[138:139], v99, off offset:96
.LBB0_790:
	s_or_b64 exec, exec, s[4:5]
	v_add_co_u32_e32 v98, vcc, 0x30000, v178
	s_mov_b32 s4, 0x14000
	s_nop 0
	v_addc_co_u32_e32 v99, vcc, 0, v179, vcc
	s_waitcnt lgkmcnt(1)
	v_add_co_u32_e32 v100, vcc, 0x38000, v178
	s_waitcnt lgkmcnt(0)
	s_nop 0
	v_addc_co_u32_e32 v101, vcc, 0, v179, vcc
	global_load_dwordx4 v[110:113], v[98:99], off nt
	global_load_dwordx4 v[102:105], v[98:99], off offset:512 nt
	global_load_dwordx4 v[106:109], v[100:101], off nt
	s_nop 0
	global_load_dwordx4 v[98:101], v[100:101], off offset:512 nt
	ds_write_b128 v190, v[94:97]
	ds_write_b128 v191, v[90:93]
	ds_read_b128 v[90:93], v192
	v_add_co_u32_e32 v96, vcc, s55, v180
	s_waitcnt vmcnt(11) lgkmcnt(0)
	v_pk_add_f32 v[92:93], v[136:137], v[92:93]
	v_pk_add_f32 v[90:91], v[134:135], v[90:91]
	v_mul_f32_e32 v95, v93, v93
	v_mul_f32_e32 v94, v91, v91
	v_fmac_f32_e32 v94, v90, v90
	v_fmac_f32_e32 v95, v92, v92
	v_add_f32_e32 v122, v94, v95
	v_cvt_pk_bf16_f32 v94, v90, v91
	v_cvt_pk_bf16_f32 v95, v92, v93
	ds_read_b128 v[90:93], v192 offset:1024
	v_addc_co_u32_e32 v97, vcc, 0, v181, vcc
	global_store_dwordx2 v[96:97], v[94:95], off sc1
	s_waitcnt vmcnt(10) lgkmcnt(0)
	v_pk_add_f32 v[90:91], v[130:131], v[90:91]
	s_nop 0
	v_mul_f32_e32 v94, v91, v91
	v_pk_add_f32 v[92:93], v[132:133], v[92:93]
	v_fmac_f32_e32 v94, v90, v90
	v_cvt_pk_bf16_f32 v90, v90, v91
	v_cvt_pk_bf16_f32 v91, v92, v93
	ds_write_b128 v190, v[86:89]
	ds_write_b128 v191, v[82:85]
	ds_read_b128 v[82:85], v192
	v_mul_f32_e32 v95, v93, v93
	v_add_co_u32_e32 v86, vcc, s4, v180
	v_fmac_f32_e32 v95, v92, v92
	s_waitcnt lgkmcnt(0)
	v_pk_add_f32 v[82:83], v[118:119], v[82:83]
	v_addc_co_u32_e32 v87, vcc, 0, v181, vcc
	v_mul_f32_e32 v92, v83, v83
	global_store_dwordx2 v[86:87], v[90:91], off sc1
	v_pk_add_f32 v[88:89], v[120:121], v[84:85]
	v_fmac_f32_e32 v92, v82, v82
	v_cvt_pk_bf16_f32 v90, v82, v83
	v_cvt_pk_bf16_f32 v91, v88, v89
	ds_read_b128 v[82:85], v192 offset:1024
	v_mul_f32_e32 v89, v89, v89
	v_fmac_f32_e32 v89, v88, v88
	v_add_f32_e32 v88, v92, v89
	v_add_f32_e32 v94, v94, v95
	v_add_f32_e32 v95, v122, v88
	s_waitcnt vmcnt(10) lgkmcnt(0)
	v_pk_add_f32 v[88:89], v[116:117], v[84:85]
	v_pk_add_f32 v[92:93], v[114:115], v[82:83]
	v_mul_f32_e32 v83, v89, v89
	v_mul_f32_e32 v82, v93, v93
	v_fmac_f32_e32 v82, v92, v92
	v_fmac_f32_e32 v83, v88, v88
	v_add_f32_e32 v82, v82, v83
	v_add_f32_e32 v82, v94, v82
	ds_bpermute_b32 v83, v193, v95
	ds_bpermute_b32 v84, v193, v82
	global_store_dwordx2 v[96:97], v[90:91], off offset:256 sc1
	v_cvt_pk_bf16_f32 v90, v92, v93
	v_cvt_pk_bf16_f32 v91, v88, v89
	s_waitcnt lgkmcnt(1)
	v_add_f32_e32 v83, v95, v83
	s_waitcnt lgkmcnt(0)
	v_add_f32_e32 v84, v82, v84
	ds_bpermute_b32 v82, v140, v83
	ds_bpermute_b32 v85, v140, v84
	global_store_dwordx2 v[86:87], v[90:91], off offset:256 sc1
	s_waitcnt lgkmcnt(1)
	v_add_f32_e32 v82, v83, v82
	s_waitcnt lgkmcnt(0)
	v_add_f32_e32 v83, v84, v85
	ds_bpermute_b32 v84, v141, v82
	ds_bpermute_b32 v85, v141, v83
	s_and_saveexec_b64 s[4:5], s[0:1]
	s_cbranch_execz .LBB0_792
	s_waitcnt lgkmcnt(1)
	v_add_f32_e32 v82, v82, v84
	s_waitcnt lgkmcnt(0)
	v_add_f32_e32 v83, v83, v85
	global_atomic_add_f32 v[138:139], v82, off offset:128
	global_atomic_add_f32 v[138:139], v83, off offset:160
; __device__ __forceinline__ unsigned cvt_pk_bf16(float lo, float hi) { unsigned r; asm volatile("v_cvt_pk_bf16_f32 %0, %1, %2" : "=v"(r) : "v"(lo), "v"(hi)); return r; }
; #define LAS __attribute__((address_space(3)))
;     __device__ __forceinline__ void operator()(const pg8::f32x4 (&acc)[2][2][4][2], const Unit& u, int wr, int wc, int fr, int fq) const {
;     ...
;         for (int g = 0; g < 8; ++g) { const int ai = g >> 2, m = g & 3, rg = ai * HALF + m * 16; float s0 = 0.f, s1 = 0.f;
;             if (g < 7) { const int rgn = ((g + 1) >> 2) * HALF + ((g + 1) & 3) * 16;
; #pragma unroll
;                 for (int bj = 0; bj < 2; ++bj)
; #pragma unroll
;                     for (int p = 0; p < 2; ++p) xn[bj][p] = *(const pg8::f32x4*)(xb + (size_t)(rgn + 8 * p) * DM + bj * HALF); }
; #pragma unroll
;             for (int bj = 0; bj < 2; ++bj) { *(LAS pg8::f32x4*)epi_slot(W, fr, 2 * fq) = acc[ai][bj][m][0]; *(LAS pg8::f32x4*)epi_slot(W, fr, 2 * fq + 1) = acc[ai][bj][m][1];
; #pragma unroll
;                 for (int p = 0; p < 2; ++p) { const pg8::f32x4 x1 = xc[bj][p] + *(const LAS pg8::f32x4*)epi_slot(W, 8 * p + rr, sl);
;                     const float q = (x1[0] * x1[0] + x1[1] * x1[1]) + (x1[2] * x1[2] + x1[3] * x1[3]); if (p == 0) s0 += q; else s1 += q;
;                     v2u w; w.x = cvt_pk_bf16(x1[0], x1[1]); w.y = cvt_pk_bf16(x1[2], x1[3]); *(v2u*)(ob + (size_t)(rg + 8 * p) * DM + bj * HALF) = w; } }
;             s0 += __shfl_xor(s0, 1); s1 += __shfl_xor(s1, 1); s0 += __shfl_xor(s0, 2); s1 += __shfl_xor(s1, 2); s0 += __shfl_xor(s0, 4); s1 += __shfl_xor(s1, 4);
;             if (sl == 0) { __hip_atomic_fetch_add(SS1 + row0 + rg + rr, s0, __ATOMIC_RELAXED, __HIP_MEMORY_SCOPE_AGENT); __hip_atomic_fetch_add(SS1 + row0 + rg + 8 + rr, s1, __ATOMIC_RELAXED, __HIP_MEMORY_SCOPE_AGENT); }
; #pragma unroll
;             for (int bj = 0; bj < 2; ++bj)
; #pragma unroll
;                 for (int p = 0; p < 2; ++p) xc[bj][p] = xn[bj][p]; }
.LBB0_792:
	s_or_b64 exec, exec, s[4:5]
	v_add_co_u32_e32 v82, vcc, 0x80000, v178
	s_mov_b32 s4, 0x1c000
	s_nop 0
	v_addc_co_u32_e32 v83, vcc, 0, v179, vcc
	s_waitcnt lgkmcnt(1)
	v_add_co_u32_e32 v84, vcc, 0x88000, v178
	s_waitcnt lgkmcnt(0)
	s_nop 0
	v_addc_co_u32_e32 v85, vcc, 0, v179, vcc
	global_load_dwordx4 v[94:97], v[82:83], off nt
	global_load_dwordx4 v[86:89], v[82:83], off offset:512 nt
	global_load_dwordx4 v[90:93], v[84:85], off nt
	s_nop 0
	global_load_dwordx4 v[82:85], v[84:85], off offset:512 nt
	ds_write_b128 v190, v[78:81]
	ds_write_b128 v191, v[74:77]
	ds_read_b128 v[74:77], v192
	v_add_co_u32_e32 v80, vcc, s63, v180
	s_waitcnt vmcnt(11) lgkmcnt(0)
	v_pk_add_f32 v[76:77], v[112:113], v[76:77]
	v_pk_add_f32 v[74:75], v[110:111], v[74:75]
	v_mul_f32_e32 v79, v77, v77
	v_mul_f32_e32 v78, v75, v75
	v_fmac_f32_e32 v78, v74, v74
	v_fmac_f32_e32 v79, v76, v76
	v_add_f32_e32 v110, v78, v79
	v_cvt_pk_bf16_f32 v78, v74, v75
	v_cvt_pk_bf16_f32 v79, v76, v77
	ds_read_b128 v[74:77], v192 offset:1024
	v_addc_co_u32_e32 v81, vcc, 0, v181, vcc
	global_store_dwordx2 v[80:81], v[78:79], off sc1
	s_waitcnt vmcnt(10) lgkmcnt(0)
	v_pk_add_f32 v[74:75], v[106:107], v[74:75]
	s_nop 0
	v_mul_f32_e32 v78, v75, v75
	v_pk_add_f32 v[76:77], v[108:109], v[76:77]
	v_fmac_f32_e32 v78, v74, v74
	v_cvt_pk_bf16_f32 v74, v74, v75
	v_cvt_pk_bf16_f32 v75, v76, v77
	ds_write_b128 v190, v[70:73]
	ds_write_b128 v191, v[66:69]
	ds_read_b128 v[66:69], v192
	v_mul_f32_e32 v79, v77, v77
	v_add_co_u32_e32 v70, vcc, s4, v180
	v_fmac_f32_e32 v79, v76, v76
	s_waitcnt lgkmcnt(0)
	v_pk_add_f32 v[66:67], v[102:103], v[66:67]
	v_addc_co_u32_e32 v71, vcc, 0, v181, vcc
	v_mul_f32_e32 v76, v67, v67
	global_store_dwordx2 v[70:71], v[74:75], off sc1
	v_pk_add_f32 v[72:73], v[104:105], v[68:69]
	v_fmac_f32_e32 v76, v66, v66
	v_cvt_pk_bf16_f32 v74, v66, v67
	v_cvt_pk_bf16_f32 v75, v72, v73
	ds_read_b128 v[66:69], v192 offset:1024
	v_mul_f32_e32 v73, v73, v73
	v_fmac_f32_e32 v73, v72, v72
	v_add_f32_e32 v72, v76, v73
	v_add_f32_e32 v78, v78, v79
	v_add_f32_e32 v79, v110, v72
	s_waitcnt vmcnt(10) lgkmcnt(0)
	v_pk_add_f32 v[72:73], v[100:101], v[68:69]
	v_pk_add_f32 v[76:77], v[98:99], v[66:67]
	v_mul_f32_e32 v67, v73, v73
	v_mul_f32_e32 v66, v77, v77
	v_fmac_f32_e32 v66, v76, v76
	v_fmac_f32_e32 v67, v72, v72
	v_add_f32_e32 v66, v66, v67
	v_add_f32_e32 v66, v78, v66
	ds_bpermute_b32 v67, v193, v79
	ds_bpermute_b32 v68, v193, v66
	global_store_dwordx2 v[80:81], v[74:75], off offset:256 sc1
	v_cvt_pk_bf16_f32 v74, v76, v77
	v_cvt_pk_bf16_f32 v75, v72, v73
	s_waitcnt lgkmcnt(1)
	v_add_f32_e32 v67, v79, v67
	s_waitcnt lgkmcnt(0)
	v_add_f32_e32 v68, v66, v68
	ds_bpermute_b32 v66, v140, v67
	ds_bpermute_b32 v69, v140, v68
	global_store_dwordx2 v[70:71], v[74:75], off offset:256 sc1
	s_waitcnt lgkmcnt(1)
	v_add_f32_e32 v66, v67, v66
	s_waitcnt lgkmcnt(0)
	v_add_f32_e32 v67, v68, v69
	ds_bpermute_b32 v68, v141, v66
	ds_bpermute_b32 v69, v141, v67
	s_and_saveexec_b64 s[4:5], s[0:1]
	s_cbranch_execz .LBB0_794
	s_waitcnt lgkmcnt(1)
	v_add_f32_e32 v66, v66, v68
	s_waitcnt lgkmcnt(0)
	v_add_f32_e32 v67, v67, v69
	global_atomic_add_f32 v[138:139], v66, off offset:192
	global_atomic_add_f32 v[138:139], v67, off offset:224
.LBB0_794:
	s_or_b64 exec, exec, s[4:5]
	v_add_co_u32_e32 v66, vcc, 0x90000, v178
	s_mov_b32 s4, 0x40000
	s_nop 0
	v_addc_co_u32_e32 v67, vcc, 0, v179, vcc
	s_waitcnt lgkmcnt(1)
	v_add_co_u32_e32 v68, vcc, 0x98000, v178
	s_waitcnt lgkmcnt(0)
	s_nop 0
	v_addc_co_u32_e32 v69, vcc, 0, v179, vcc
	global_load_dwordx4 v[78:81], v[66:67], off nt
	global_load_dwordx4 v[70:73], v[66:67], off offset:512 nt
	global_load_dwordx4 v[74:77], v[68:69], off nt
	s_nop 0
	global_load_dwordx4 v[66:69], v[68:69], off offset:512 nt
	ds_write_b128 v190, v[62:65]
	ds_write_b128 v191, v[58:61]
	ds_read_b128 v[58:61], v192
	v_add_co_u32_e32 v64, vcc, s4, v180
	s_mov_b32 s4, 0x44000
	s_nop 0
	v_addc_co_u32_e32 v65, vcc, 0, v181, vcc
	s_waitcnt vmcnt(11) lgkmcnt(0)
	v_pk_add_f32 v[60:61], v[96:97], v[60:61]
	v_pk_add_f32 v[58:59], v[94:95], v[58:59]
	v_mul_f32_e32 v63, v61, v61
	v_mul_f32_e32 v62, v59, v59
	v_fmac_f32_e32 v62, v58, v58
	v_fmac_f32_e32 v63, v60, v60
	v_add_f32_e32 v94, v62, v63
	v_cvt_pk_bf16_f32 v62, v58, v59
	v_cvt_pk_bf16_f32 v63, v60, v61
	ds_read_b128 v[58:61], v192 offset:1024
	global_store_dwordx2 v[64:65], v[62:63], off sc1
	s_waitcnt vmcnt(10) lgkmcnt(0)
	v_pk_add_f32 v[58:59], v[90:91], v[58:59]
	s_nop 0
	v_mul_f32_e32 v62, v59, v59
	v_pk_add_f32 v[60:61], v[92:93], v[60:61]
	v_fmac_f32_e32 v62, v58, v58
	v_cvt_pk_bf16_f32 v58, v58, v59
	v_cvt_pk_bf16_f32 v59, v60, v61
	ds_write_b128 v190, v[54:57]
	ds_write_b128 v191, v[50:53]
	ds_read_b128 v[50:53], v192
	v_mul_f32_e32 v63, v61, v61
	v_add_co_u32_e32 v54, vcc, s4, v180
	v_fmac_f32_e32 v63, v60, v60
	s_waitcnt lgkmcnt(0)
	v_pk_add_f32 v[50:51], v[86:87], v[50:51]
	v_addc_co_u32_e32 v55, vcc, 0, v181, vcc
	v_mul_f32_e32 v60, v51, v51
	global_store_dwordx2 v[54:55], v[58:59], off sc1
	v_pk_add_f32 v[56:57], v[88:89], v[52:53]
	v_fmac_f32_e32 v60, v50, v50
	v_cvt_pk_bf16_f32 v58, v50, v51
	v_cvt_pk_bf16_f32 v59, v56, v57
	ds_read_b128 v[50:53], v192 offset:1024
	v_mul_f32_e32 v57, v57, v57
	v_fmac_f32_e32 v57, v56, v56
	v_add_f32_e32 v56, v60, v57
	v_add_f32_e32 v62, v62, v63
	v_add_f32_e32 v63, v94, v56
	s_waitcnt vmcnt(10) lgkmcnt(0)
	v_pk_add_f32 v[56:57], v[84:85], v[52:53]
	v_pk_add_f32 v[60:61], v[82:83], v[50:51]
	v_mul_f32_e32 v51, v57, v57
	v_mul_f32_e32 v50, v61, v61
	v_fmac_f32_e32 v50, v60, v60
	v_fmac_f32_e32 v51, v56, v56
	v_add_f32_e32 v50, v50, v51
	v_add_f32_e32 v50, v62, v50
	ds_bpermute_b32 v51, v193, v63
	ds_bpermute_b32 v52, v193, v50
	global_store_dwordx2 v[64:65], v[58:59], off offset:256 sc1
	v_cvt_pk_bf16_f32 v58, v60, v61
	v_cvt_pk_bf16_f32 v59, v56, v57
	s_waitcnt lgkmcnt(1)
	v_add_f32_e32 v51, v63, v51
	s_waitcnt lgkmcnt(0)
	v_add_f32_e32 v52, v50, v52
	ds_bpermute_b32 v50, v140, v51
	ds_bpermute_b32 v53, v140, v52
	global_store_dwordx2 v[54:55], v[58:59], off offset:256 sc1
	s_waitcnt lgkmcnt(1)
	v_add_f32_e32 v50, v51, v50
	s_waitcnt lgkmcnt(0)
	v_add_f32_e32 v51, v52, v53
	ds_bpermute_b32 v52, v141, v50
	ds_bpermute_b32 v53, v141, v51
	s_and_saveexec_b64 s[4:5], s[0:1]
	s_cbranch_execz .LBB0_796
	s_waitcnt lgkmcnt(1)
	v_add_f32_e32 v50, v50, v52
	s_waitcnt lgkmcnt(0)
	v_add_f32_e32 v51, v51, v53
	global_atomic_add_f32 v[138:139], v50, off offset:512
	global_atomic_add_f32 v[138:139], v51, off offset:544
; __device__ __forceinline__ unsigned cvt_pk_bf16(float lo, float hi) { unsigned r; asm volatile("v_cvt_pk_bf16_f32 %0, %1, %2" : "=v"(r) : "v"(lo), "v"(hi)); return r; }
; #define LAS __attribute__((address_space(3)))
;     __device__ __forceinline__ void operator()(const pg8::f32x4 (&acc)[2][2][4][2], const Unit& u, int wr, int wc, int fr, int fq) const {
;     ...
;         for (int g = 0; g < 8; ++g) { const int ai = g >> 2, m = g & 3, rg = ai * HALF + m * 16; float s0 = 0.f, s1 = 0.f;
;             if (g < 7) { const int rgn = ((g + 1) >> 2) * HALF + ((g + 1) & 3) * 16;
; #pragma unroll
;                 for (int bj = 0; bj < 2; ++bj)
; #pragma unroll
;                     for (int p = 0; p < 2; ++p) xn[bj][p] = *(const pg8::f32x4*)(xb + (size_t)(rgn + 8 * p) * DM + bj * HALF); }
; #pragma unroll
;             for (int bj = 0; bj < 2; ++bj) { *(LAS pg8::f32x4*)epi_slot(W, fr, 2 * fq) = acc[ai][bj][m][0]; *(LAS pg8::f32x4*)epi_slot(W, fr, 2 * fq + 1) = acc[ai][bj][m][1];
; #pragma unroll
;                 for (int p = 0; p < 2; ++p) { const pg8::f32x4 x1 = xc[bj][p] + *(const LAS pg8::f32x4*)epi_slot(W, 8 * p + rr, sl);
;                     const float q = (x1[0] * x1[0] + x1[1] * x1[1]) + (x1[2] * x1[2] + x1[3] * x1[3]); if (p == 0) s0 += q; else s1 += q;
;                     v2u w; w.x = cvt_pk_bf16(x1[0], x1[1]); w.y = cvt_pk_bf16(x1[2], x1[3]); *(v2u*)(ob + (size_t)(rg + 8 * p) * DM + bj * HALF) = w; } }
;             s0 += __shfl_xor(s0, 1); s1 += __shfl_xor(s1, 1); s0 += __shfl_xor(s0, 2); s1 += __shfl_xor(s1, 2); s0 += __shfl_xor(s0, 4); s1 += __shfl_xor(s1, 4);
;             if (sl == 0) { __hip_atomic_fetch_add(SS1 + row0 + rg + rr, s0, __ATOMIC_RELAXED, __HIP_MEMORY_SCOPE_AGENT); __hip_atomic_fetch_add(SS1 + row0 + rg + 8 + rr, s1, __ATOMIC_RELAXED, __HIP_MEMORY_SCOPE_AGENT); }
; #pragma unroll
;             for (int bj = 0; bj < 2; ++bj)
; #pragma unroll
;                 for (int p = 0; p < 2; ++p) xc[bj][p] = xn[bj][p]; }
.LBB0_796:
	s_or_b64 exec, exec, s[4:5]
	v_add_co_u32_e32 v50, vcc, 0xa0000, v178
	s_mov_b32 s4, 0x48000
	s_nop 0
	v_addc_co_u32_e32 v51, vcc, 0, v179, vcc
	s_waitcnt lgkmcnt(1)
	v_add_co_u32_e32 v52, vcc, 0xa8000, v178
	s_waitcnt lgkmcnt(0)
	s_nop 0
	v_addc_co_u32_e32 v53, vcc, 0, v179, vcc
	global_load_dwordx4 v[62:65], v[50:51], off nt
	global_load_dwordx4 v[54:57], v[50:51], off offset:512 nt
	global_load_dwordx4 v[58:61], v[52:53], off nt
	s_nop 0
	global_load_dwordx4 v[50:53], v[52:53], off offset:512 nt
	ds_write_b128 v190, v[46:49]
	ds_write_b128 v191, v[42:45]
	ds_read_b128 v[42:45], v192
	v_add_co_u32_e32 v48, vcc, s4, v180
	s_mov_b32 s4, 0x4c000
	s_nop 0
	v_addc_co_u32_e32 v49, vcc, 0, v181, vcc
	s_waitcnt vmcnt(11) lgkmcnt(0)
	v_pk_add_f32 v[44:45], v[80:81], v[44:45]
	v_pk_add_f32 v[42:43], v[78:79], v[42:43]
	v_mul_f32_e32 v47, v45, v45
	v_mul_f32_e32 v46, v43, v43
	v_fmac_f32_e32 v46, v42, v42
	v_fmac_f32_e32 v47, v44, v44
	v_add_f32_e32 v78, v46, v47
	v_cvt_pk_bf16_f32 v46, v42, v43
	v_cvt_pk_bf16_f32 v47, v44, v45
	ds_read_b128 v[42:45], v192 offset:1024
	global_store_dwordx2 v[48:49], v[46:47], off sc1
	s_waitcnt vmcnt(10) lgkmcnt(0)
	v_pk_add_f32 v[42:43], v[74:75], v[42:43]
	s_nop 0
	v_mul_f32_e32 v46, v43, v43
	v_pk_add_f32 v[44:45], v[76:77], v[44:45]
	v_fmac_f32_e32 v46, v42, v42
	v_cvt_pk_bf16_f32 v42, v42, v43
	v_cvt_pk_bf16_f32 v43, v44, v45
	ds_write_b128 v190, v[38:41]
	ds_write_b128 v191, v[34:37]
	ds_read_b128 v[34:37], v192
	v_mul_f32_e32 v47, v45, v45
	v_add_co_u32_e32 v38, vcc, s4, v180
	v_fmac_f32_e32 v47, v44, v44
	s_waitcnt lgkmcnt(0)
	v_pk_add_f32 v[34:35], v[70:71], v[34:35]
	v_addc_co_u32_e32 v39, vcc, 0, v181, vcc
	v_mul_f32_e32 v44, v35, v35
	global_store_dwordx2 v[38:39], v[42:43], off sc1
	v_pk_add_f32 v[40:41], v[72:73], v[36:37]
	v_fmac_f32_e32 v44, v34, v34
	v_cvt_pk_bf16_f32 v42, v34, v35
	v_cvt_pk_bf16_f32 v43, v40, v41
	ds_read_b128 v[34:37], v192 offset:1024
	v_mul_f32_e32 v41, v41, v41
	v_fmac_f32_e32 v41, v40, v40
	v_add_f32_e32 v40, v44, v41
	v_add_f32_e32 v46, v46, v47
	v_add_f32_e32 v47, v78, v40
	s_waitcnt vmcnt(10) lgkmcnt(0)
	v_pk_add_f32 v[40:41], v[68:69], v[36:37]
	v_pk_add_f32 v[44:45], v[66:67], v[34:35]
	v_mul_f32_e32 v35, v41, v41
	v_mul_f32_e32 v34, v45, v45
	v_fmac_f32_e32 v34, v44, v44
	v_fmac_f32_e32 v35, v40, v40
	v_add_f32_e32 v34, v34, v35
	v_add_f32_e32 v34, v46, v34
	ds_bpermute_b32 v35, v193, v47
	ds_bpermute_b32 v36, v193, v34
	global_store_dwordx2 v[48:49], v[42:43], off offset:256 sc1
	v_cvt_pk_bf16_f32 v42, v44, v45
	v_cvt_pk_bf16_f32 v43, v40, v41
	s_waitcnt lgkmcnt(1)
	v_add_f32_e32 v35, v47, v35
	s_waitcnt lgkmcnt(0)
	v_add_f32_e32 v36, v34, v36
	ds_bpermute_b32 v34, v140, v35
	ds_bpermute_b32 v37, v140, v36
	global_store_dwordx2 v[38:39], v[42:43], off offset:256 sc1
	s_waitcnt lgkmcnt(1)
	v_add_f32_e32 v34, v35, v34
	s_waitcnt lgkmcnt(0)
	v_add_f32_e32 v35, v36, v37
	ds_bpermute_b32 v36, v141, v34
	ds_bpermute_b32 v37, v141, v35
	s_and_saveexec_b64 s[4:5], s[0:1]
	s_cbranch_execz .LBB0_798
	s_waitcnt lgkmcnt(1)
	v_add_f32_e32 v34, v34, v36
	s_waitcnt lgkmcnt(0)
	v_add_f32_e32 v35, v35, v37
	global_atomic_add_f32 v[138:139], v34, off offset:576
	global_atomic_add_f32 v[138:139], v35, off offset:608
; __device__ __forceinline__ unsigned cvt_pk_bf16(float lo, float hi) { unsigned r; asm volatile("v_cvt_pk_bf16_f32 %0, %1, %2" : "=v"(r) : "v"(lo), "v"(hi)); return r; }
; #define LAS __attribute__((address_space(3)))
;     __device__ __forceinline__ void operator()(const pg8::f32x4 (&acc)[2][2][4][2], const Unit& u, int wr, int wc, int fr, int fq) const {
;     ...
;         for (int g = 0; g < 8; ++g) { const int ai = g >> 2, m = g & 3, rg = ai * HALF + m * 16; float s0 = 0.f, s1 = 0.f;
;             if (g < 7) { const int rgn = ((g + 1) >> 2) * HALF + ((g + 1) & 3) * 16;
; #pragma unroll
;                 for (int bj = 0; bj < 2; ++bj)
; #pragma unroll
;                     for (int p = 0; p < 2; ++p) xn[bj][p] = *(const pg8::f32x4*)(xb + (size_t)(rgn + 8 * p) * DM + bj * HALF); }
; #pragma unroll
;             for (int bj = 0; bj < 2; ++bj) { *(LAS pg8::f32x4*)epi_slot(W, fr, 2 * fq) = acc[ai][bj][m][0]; *(LAS pg8::f32x4*)epi_slot(W, fr, 2 * fq + 1) = acc[ai][bj][m][1];
; #pragma unroll
;                 for (int p = 0; p < 2; ++p) { const pg8::f32x4 x1 = xc[bj][p] + *(const LAS pg8::f32x4*)epi_slot(W, 8 * p + rr, sl);
;                     const float q = (x1[0] * x1[0] + x1[1] * x1[1]) + (x1[2] * x1[2] + x1[3] * x1[3]); if (p == 0) s0 += q; else s1 += q;
;                     v2u w; w.x = cvt_pk_bf16(x1[0], x1[1]); w.y = cvt_pk_bf16(x1[2], x1[3]); *(v2u*)(ob + (size_t)(rg + 8 * p) * DM + bj * HALF) = w; } }
;             s0 += __shfl_xor(s0, 1); s1 += __shfl_xor(s1, 1); s0 += __shfl_xor(s0, 2); s1 += __shfl_xor(s1, 2); s0 += __shfl_xor(s0, 4); s1 += __shfl_xor(s1, 4);
;             if (sl == 0) { __hip_atomic_fetch_add(SS1 + row0 + rg + rr, s0, __ATOMIC_RELAXED, __HIP_MEMORY_SCOPE_AGENT); __hip_atomic_fetch_add(SS1 + row0 + rg + 8 + rr, s1, __ATOMIC_RELAXED, __HIP_MEMORY_SCOPE_AGENT); }
; #pragma unroll
;             for (int bj = 0; bj < 2; ++bj)
; #pragma unroll
;                 for (int p = 0; p < 2; ++p) xc[bj][p] = xn[bj][p]; }
.LBB0_798:
	s_or_b64 exec, exec, s[4:5]
	v_add_co_u32_e32 v34, vcc, 0xb0000, v178
	s_mov_b32 s4, 0x50000
	s_nop 0
	v_addc_co_u32_e32 v35, vcc, 0, v179, vcc
	s_waitcnt lgkmcnt(1)
	v_add_co_u32_e32 v36, vcc, 0xb8000, v178
	s_waitcnt lgkmcnt(0)
	s_nop 0
	v_addc_co_u32_e32 v37, vcc, 0, v179, vcc
	global_load_dwordx4 v[46:49], v[34:35], off nt
	global_load_dwordx4 v[38:41], v[34:35], off offset:512 nt
	global_load_dwordx4 v[42:45], v[36:37], off nt
	s_nop 0
	global_load_dwordx4 v[34:37], v[36:37], off offset:512 nt
	ds_write_b128 v190, v[30:33]
	ds_write_b128 v191, v[26:29]
	ds_read_b128 v[26:29], v192
	v_add_co_u32_e32 v32, vcc, s4, v180
	s_mov_b32 s4, 0x54000
	s_nop 0
	v_addc_co_u32_e32 v33, vcc, 0, v181, vcc
	s_waitcnt vmcnt(11) lgkmcnt(0)
	v_pk_add_f32 v[28:29], v[64:65], v[28:29]
	v_pk_add_f32 v[26:27], v[62:63], v[26:27]
	v_mul_f32_e32 v31, v29, v29
	v_mul_f32_e32 v30, v27, v27
	v_fmac_f32_e32 v30, v26, v26
	v_fmac_f32_e32 v31, v28, v28
	v_add_f32_e32 v62, v30, v31
	v_cvt_pk_bf16_f32 v30, v26, v27
	v_cvt_pk_bf16_f32 v31, v28, v29
	ds_read_b128 v[26:29], v192 offset:1024
	global_store_dwordx2 v[32:33], v[30:31], off sc1
	s_waitcnt vmcnt(10) lgkmcnt(0)
	v_pk_add_f32 v[26:27], v[58:59], v[26:27]
	s_nop 0
	v_mul_f32_e32 v30, v27, v27
	v_pk_add_f32 v[28:29], v[60:61], v[28:29]
	v_fmac_f32_e32 v30, v26, v26
	v_cvt_pk_bf16_f32 v26, v26, v27
	v_cvt_pk_bf16_f32 v27, v28, v29
	ds_write_b128 v190, v[22:25]
	ds_write_b128 v191, v[18:21]
	ds_read_b128 v[18:21], v192
	v_mul_f32_e32 v31, v29, v29
	v_add_co_u32_e32 v22, vcc, s4, v180
	v_fmac_f32_e32 v31, v28, v28
	s_waitcnt lgkmcnt(0)
	v_pk_add_f32 v[18:19], v[54:55], v[18:19]
	v_addc_co_u32_e32 v23, vcc, 0, v181, vcc
	v_mul_f32_e32 v28, v19, v19
	global_store_dwordx2 v[22:23], v[26:27], off sc1
	v_pk_add_f32 v[24:25], v[56:57], v[20:21]
	v_fmac_f32_e32 v28, v18, v18
	v_cvt_pk_bf16_f32 v26, v18, v19
	v_cvt_pk_bf16_f32 v27, v24, v25
	ds_read_b128 v[18:21], v192 offset:1024
	v_mul_f32_e32 v25, v25, v25
	v_fmac_f32_e32 v25, v24, v24
	v_add_f32_e32 v24, v28, v25
	v_add_f32_e32 v30, v30, v31
	v_add_f32_e32 v31, v62, v24
	s_waitcnt vmcnt(10) lgkmcnt(0)
	v_pk_add_f32 v[24:25], v[52:53], v[20:21]
	v_pk_add_f32 v[28:29], v[50:51], v[18:19]
	v_mul_f32_e32 v19, v25, v25
	v_mul_f32_e32 v18, v29, v29
	v_fmac_f32_e32 v18, v28, v28
	v_fmac_f32_e32 v19, v24, v24
	v_add_f32_e32 v18, v18, v19
	v_add_f32_e32 v18, v30, v18
	ds_bpermute_b32 v19, v193, v31
	ds_bpermute_b32 v20, v193, v18
	global_store_dwordx2 v[32:33], v[26:27], off offset:256 sc1
	v_cvt_pk_bf16_f32 v26, v28, v29
	v_cvt_pk_bf16_f32 v27, v24, v25
	s_waitcnt lgkmcnt(1)
	v_add_f32_e32 v19, v31, v19
	s_waitcnt lgkmcnt(0)
	v_add_f32_e32 v20, v18, v20
	ds_bpermute_b32 v18, v140, v19
	ds_bpermute_b32 v21, v140, v20
	global_store_dwordx2 v[22:23], v[26:27], off offset:256 sc1
	s_waitcnt lgkmcnt(1)
	v_add_f32_e32 v18, v19, v18
	s_waitcnt lgkmcnt(0)
	v_add_f32_e32 v19, v20, v21
	ds_bpermute_b32 v20, v141, v18
	ds_bpermute_b32 v21, v141, v19
	s_and_saveexec_b64 s[4:5], s[0:1]
	s_cbranch_execz .LBB0_800
	s_waitcnt lgkmcnt(1)
	v_add_f32_e32 v18, v18, v20
	s_waitcnt lgkmcnt(0)
	v_add_f32_e32 v19, v19, v21
	global_atomic_add_f32 v[138:139], v18, off offset:640
	global_atomic_add_f32 v[138:139], v19, off offset:672
.LBB0_800:
	s_or_b64 exec, exec, s[4:5]
	ds_write_b128 v190, v[14:17]
	ds_write_b128 v191, v[10:13]
	ds_read_b128 v[10:13], v192
	s_mov_b32 s4, 0x58000
	v_add_co_u32_e32 v16, vcc, s4, v180
	s_mov_b32 s4, 0x5c000
	s_waitcnt vmcnt(7) lgkmcnt(0)
	v_pk_add_f32 v[12:13], v[48:49], v[12:13]
	v_pk_add_f32 v[10:11], v[46:47], v[10:11]
	v_mul_f32_e32 v15, v13, v13
	v_mul_f32_e32 v14, v11, v11
	v_fmac_f32_e32 v14, v10, v10
	v_fmac_f32_e32 v15, v12, v12
	v_add_f32_e32 v18, v14, v15
	v_cvt_pk_bf16_f32 v14, v10, v11
	v_cvt_pk_bf16_f32 v15, v12, v13
	ds_read_b128 v[10:13], v192 offset:1024
	v_addc_co_u32_e32 v17, vcc, 0, v181, vcc
	global_store_dwordx2 v[16:17], v[14:15], off sc1
	s_waitcnt vmcnt(6) lgkmcnt(0)
	v_pk_add_f32 v[10:11], v[42:43], v[10:11]
	s_nop 0
	v_mul_f32_e32 v14, v11, v11
	v_pk_add_f32 v[12:13], v[44:45], v[12:13]
	v_fmac_f32_e32 v14, v10, v10
	v_cvt_pk_bf16_f32 v10, v10, v11
	v_cvt_pk_bf16_f32 v11, v12, v13
	ds_write_b128 v190, v[6:9]
	ds_write_b128 v191, v[2:5]
	ds_read_b128 v[2:5], v192
	v_mul_f32_e32 v15, v13, v13
	v_add_co_u32_e32 v6, vcc, s4, v180
	v_fmac_f32_e32 v15, v12, v12
	s_waitcnt lgkmcnt(0)
	v_pk_add_f32 v[2:3], v[38:39], v[2:3]
	v_addc_co_u32_e32 v7, vcc, 0, v181, vcc
	v_mul_f32_e32 v12, v3, v3
	global_store_dwordx2 v[6:7], v[10:11], off sc1
	v_pk_add_f32 v[8:9], v[40:41], v[4:5]
	v_fmac_f32_e32 v12, v2, v2
	v_cvt_pk_bf16_f32 v10, v2, v3
	v_cvt_pk_bf16_f32 v11, v8, v9
	ds_read_b128 v[2:5], v192 offset:1024
	v_mul_f32_e32 v9, v9, v9
	v_fmac_f32_e32 v9, v8, v8
	v_add_f32_e32 v8, v12, v9
	v_add_f32_e32 v14, v14, v15
	v_add_f32_e32 v15, v18, v8
	s_waitcnt vmcnt(6) lgkmcnt(0)
	v_pk_add_f32 v[8:9], v[36:37], v[4:5]
	v_pk_add_f32 v[12:13], v[34:35], v[2:3]
	v_mul_f32_e32 v3, v9, v9
	v_mul_f32_e32 v2, v13, v13
	v_fmac_f32_e32 v2, v12, v12
	v_fmac_f32_e32 v3, v8, v8
	v_add_f32_e32 v2, v2, v3
	v_add_f32_e32 v2, v14, v2
	ds_bpermute_b32 v3, v193, v15
	ds_bpermute_b32 v4, v193, v2
	global_store_dwordx2 v[16:17], v[10:11], off offset:256 sc1
	v_cvt_pk_bf16_f32 v10, v12, v13
	v_cvt_pk_bf16_f32 v11, v8, v9
	s_waitcnt lgkmcnt(1)
	v_add_f32_e32 v3, v15, v3
	s_waitcnt lgkmcnt(0)
	v_add_f32_e32 v4, v2, v4
	ds_bpermute_b32 v2, v140, v3
	ds_bpermute_b32 v5, v140, v4
	global_store_dwordx2 v[6:7], v[10:11], off offset:256 sc1
	s_waitcnt lgkmcnt(1)
	v_add_f32_e32 v2, v3, v2
	s_waitcnt lgkmcnt(0)
	v_add_f32_e32 v3, v4, v5
	ds_bpermute_b32 v4, v141, v2
	ds_bpermute_b32 v5, v141, v3
	s_and_saveexec_b64 s[4:5], s[0:1]
	s_cbranch_execz .LBB0_802
	s_waitcnt lgkmcnt(1)
	v_add_f32_e32 v2, v2, v4
	s_waitcnt lgkmcnt(0)
	v_add_f32_e32 v3, v3, v5
	global_atomic_add_f32 v[138:139], v2, off offset:704
	global_atomic_add_f32 v[138:139], v3, off offset:736
